# prepass: even waves do both W_bc halves beside the streaming jobs, no W_bc tail in the second pass
# baseline (speedup 1.0000x reference)
.LBB0_8:
	s_mov_b32 s3, 2
	s_mov_b64 s[60:61], 0
	s_and_b64 vcc, exec, s[12:13]
	s_cbranch_vccnz .LBB0_53
.LBB0_9:
	v_cmp_eq_u32_e32 vcc, s3, v71
	s_and_saveexec_b64 s[62:63], vcc
	s_cbranch_execz .LBB0_15
	s_and_b64 exec, exec, s[6:7]
	s_cbranch_execz .LBB0_15
	s_load_dwordx2 s[12:13], s[44:45], 0x68
	s_load_dwordx4 s[28:31], s[44:45], 0x58
	s_mov_b64 s[64:65], 0
	v_mov_b32_e32 v64, v106
	v_mov_b32_e32 v65, v184
	s_mov_b32 s98, 0
	s_waitcnt lgkmcnt(0)
	s_add_u32 s35, s12, 0xf000
	s_addc_u32 s92, s13, 0

.LBB0_13:
	v_add_co_u32_e32 v16, vcc, 0xffff1000, v24
	s_add_u32 s68, s96, s66
	s_nop 0
	v_addc_co_u32_e32 v17, vcc, -1, v25, vcc
	v_add_co_u32_e32 v18, vcc, 0xffff2000, v24
	s_addc_u32 s69, s97, s67
	s_nop 0
	v_addc_co_u32_e32 v19, vcc, -1, v25, vcc
	v_add_co_u32_e32 v54, vcc, 0xffff3000, v24
	s_add_u32 s70, s94, s66
	s_nop 0
	v_addc_co_u32_e32 v55, vcc, -1, v25, vcc
	v_add_co_u32_e32 v56, vcc, 0xffff4000, v24
	s_addc_u32 s71, s95, s67
	global_load_dwordx4 v[12:15], v3, s[68:69]
	global_load_dwordx4 v[20:23], v3, s[68:69] offset:16
	global_load_dword v2, v[16:17], off
	global_load_dword v96, v[18:19], off
	s_mov_b64 s[12:13], vcc
	global_load_dwordx4 v[16:19], v3, s[70:71]
	global_load_dwordx4 v[26:29], v3, s[70:71] offset:1024
	global_load_dwordx4 v[30:33], v3, s[70:71] offset:2048
	global_load_dwordx4 v[34:37], v3, s[70:71] offset:3072
	global_load_dwordx4 v[38:41], v83, s[70:71]
	global_load_dwordx4 v[42:45], v83, s[70:71] offset:1024
	global_load_dwordx4 v[46:49], v83, s[70:71] offset:2048
	global_load_dwordx4 v[50:53], v83, s[70:71] offset:3072
	global_load_dword v97, v[54:55], off
	v_add_co_u32_e32 v54, vcc, 0xffff5000, v24
	s_waitcnt vmcnt(4)
	v_mov_b32_e32 v68, v40
	v_addc_co_u32_e32 v55, vcc, -1, v25, vcc
	v_add_co_u32_e32 v58, vcc, 0xffff6000, v24
	s_waitcnt vmcnt(2)
	v_mov_b32_e32 v92, v46
	v_addc_co_u32_e32 v59, vcc, -1, v25, vcc
	v_add_co_u32_e32 v60, vcc, 0xffff7000, v24
	global_load_dword v62, v[54:55], off
	global_load_dword v63, v[58:59], off
	v_addc_co_u32_e32 v61, vcc, -1, v25, vcc
	v_add_co_u32_e32 v54, vcc, 0xffff8000, v24
	s_waitcnt vmcnt(3)
	v_mov_b32_e32 v93, v50
	v_addc_co_u32_e32 v55, vcc, -1, v25, vcc
	v_addc_co_u32_e64 v57, vcc, -1, v25, s[12:13]
	global_load_dword v66, v[60:61], off
	global_load_dword v67, v[54:55], off
	v_mov_b32_e32 v54, v16
	global_load_dword v56, v[56:57], off
	v_mov_b32_e32 v55, v26
	v_mov_b32_e32 v60, v30
	v_mov_b32_e32 v61, v34
	v_mov_b32_e32 v34, v31
	v_mov_b32_e32 v30, v32
	v_mov_b32_e32 v31, v36
	v_mov_b32_e32 v36, v33
	v_mov_b32_e32 v32, v38
	v_mov_b32_e32 v33, v42
	v_mul_f32_e32 v2, v2, v12
	v_mov_b32_e32 v26, v17
	v_mov_b32_e32 v42, v39
	v_mov_b32_e32 v50, v47
	v_pk_fma_f32 v[46:47], v[2:3], v[54:55], v[8:9] op_sel_hi:[0,1,1]
	v_pk_fma_f32 v[6:7], v[2:3], v[60:61], v[6:7] op_sel_hi:[0,1,1]
	v_pk_fma_f32 v[4:5], v[2:3], v[32:33], v[4:5] op_sel_hi:[0,1,1]
	v_pk_fma_f32 v[32:33], v[2:3], v[92:93], v[10:11] op_sel_hi:[0,1,1]
	v_mul_f32_e32 v2, v96, v13
	v_mov_b32_e32 v58, v18
	v_mov_b32_e32 v59, v28
	v_mov_b32_e32 v69, v44
	v_mov_b32_e32 v94, v48
	v_mov_b32_e32 v95, v52
	s_waitcnt vmcnt(5)
	v_mul_f32_e32 v12, v97, v14
	v_pk_fma_f32 v[26:27], v[2:3], v[26:27], v[46:47] op_sel_hi:[0,1,1]
	v_pk_fma_f32 v[6:7], v[2:3], v[34:35], v[6:7] op_sel_hi:[0,1,1]
	v_pk_fma_f32 v[4:5], v[2:3], v[42:43], v[4:5] op_sel_hi:[0,1,1]
	v_pk_fma_f32 v[42:43], v[2:3], v[50:51], v[32:33] op_sel_hi:[0,1,1]
	v_mov_b32_e32 v28, v19
	v_mov_b32_e32 v52, v49
	global_load_dwordx4 v[16:19], v3, s[70:71] offset:16
	global_load_dwordx4 v[8:11], v3, s[70:71] offset:32
	v_pk_fma_f32 v[26:27], v[12:13], v[58:59], v[26:27] op_sel_hi:[0,1,1]
	global_load_dwordx4 v[46:49], v3, s[70:71] offset:1056
	v_pk_fma_f32 v[30:31], v[12:13], v[30:31], v[6:7] op_sel_hi:[0,1,1]
	v_pk_fma_f32 v[50:51], v[12:13], v[68:69], v[4:5] op_sel_hi:[0,1,1]
	v_pk_fma_f32 v[58:59], v[12:13], v[94:95], v[42:43] op_sel_hi:[0,1,1]
	v_mov_b32_e32 v44, v41
	global_load_dwordx4 v[38:41], v3, s[70:71] offset:1040
	global_load_dwordx4 v[32:35], v3, s[70:71] offset:48
	global_load_dwordx4 v[4:7], v3, s[70:71] offset:1072
	s_add_u32 s12, s70, 0x1000
	s_addc_u32 s13, s71, 0
	s_add_u32 vcc_lo, s70, 0x1400
	s_addc_u32 vcc_hi, s71, 0
	s_waitcnt vmcnt(6)
	v_mul_f32_e32 v2, v56, v15
	global_load_dwordx4 v[12:15], v3, s[70:71] offset:2064
	global_load_dwordx4 v[54:57], v3, s[70:71] offset:3088
	v_pk_fma_f32 v[94:95], v[2:3], v[44:45], v[50:51] op_sel_hi:[0,1,1]
	global_load_dwordx4 v[42:45], v3, s[70:71] offset:2080
	v_pk_fma_f32 v[96:97], v[2:3], v[52:53], v[58:59] op_sel_hi:[0,1,1]
	global_load_dwordx4 v[58:61], v3, s[70:71] offset:3104
	v_pk_fma_f32 v[68:69], v[2:3], v[28:29], v[26:27] op_sel_hi:[0,1,1]
	v_pk_fma_f32 v[92:93], v[2:3], v[36:37], v[30:31] op_sel_hi:[0,1,1]
	s_waitcnt vmcnt(9)
	v_mov_b32_e32 v98, v16
	s_waitcnt vmcnt(8)
	v_mov_b32_e32 v114, v8
	v_mov_b32_e32 v116, v10
	s_waitcnt vmcnt(7)
	v_mov_b32_e32 v115, v46
	v_mov_b32_e32 v46, v9
	v_mov_b32_e32 v117, v48
	v_mov_b32_e32 v48, v11
	global_load_dwordx4 v[8:11], v3, s[70:71] offset:3120
	s_waitcnt vmcnt(7)
	v_mov_b32_e32 v99, v38
	v_mov_b32_e32 v38, v17
	v_mov_b32_e32 v112, v18
	v_mov_b32_e32 v113, v40
	v_mov_b32_e32 v40, v19
	s_waitcnt vmcnt(6)
	v_mov_b32_e32 v26, v34
	s_waitcnt vmcnt(5)
	v_mov_b32_e32 v27, v6
	v_mov_b32_e32 v6, v35
	v_mov_b32_e32 v30, v32
	v_mov_b32_e32 v31, v4
	v_mov_b32_e32 v4, v33
	s_waitcnt vmcnt(4)
	v_mov_b32_e32 v118, v12
	s_waitcnt vmcnt(3)
	v_mov_b32_e32 v119, v54
	v_mov_b32_e32 v54, v13
	v_mov_b32_e32 v120, v14
	v_mov_b32_e32 v121, v56
	v_mov_b32_e32 v56, v15
	global_load_dwordx4 v[12:15], v3, s[70:71] offset:2096
	s_waitcnt vmcnt(3)
	v_mov_b32_e32 v122, v42
	s_waitcnt vmcnt(2)
	v_mov_b32_e32 v123, v58
	v_mov_b32_e32 v58, v43
	v_mov_b32_e32 v124, v44
	v_mov_b32_e32 v125, v60
	v_mov_b32_e32 v60, v45
	s_waitcnt vmcnt(1)
	v_mov_b32_e32 v35, v8
	v_mov_b32_e32 v29, v10
	s_waitcnt vmcnt(0)
	v_mov_b32_e32 v34, v12
	v_mov_b32_e32 v8, v13
	v_mov_b32_e32 v28, v14
	v_mov_b32_e32 v10, v15
	global_load_dwordx4 v[12:15], v3, s[12:13] offset:16
	global_load_dwordx4 v[42:45], v3, s[12:13] offset:32
	global_load_dwordx4 v[50:53], v3, vcc offset:16
	global_load_dwordx4 v[16:19], v3, vcc offset:32
	s_waitcnt vmcnt(3)
	v_mov_b32_e32 v126, v12
	v_mov_b32_e32 v128, v14
	s_waitcnt vmcnt(1)
	v_mov_b32_e32 v127, v50
	v_mov_b32_e32 v50, v13
	v_mov_b32_e32 v129, v52
	v_mov_b32_e32 v52, v15
	v_mov_b32_e32 v130, v42
	s_waitcnt vmcnt(0)
	v_mov_b32_e32 v131, v16
	v_mov_b32_e32 v16, v43
	v_mov_b32_e32 v132, v44
	v_mov_b32_e32 v133, v18
	v_mov_b32_e32 v18, v45
	global_load_dwordx4 v[42:45], v3, s[12:13] offset:48
	global_load_dwordx4 v[12:15], v3, vcc offset:48
	s_add_u32 s12, s70, 0x1800
	s_addc_u32 s13, s71, 0
	s_add_u32 s70, s70, 0x1c00
	s_addc_u32 s71, s71, 0
	s_add_i32 s3, s3, 16
	s_add_u32 s66, s66, 64
	s_addc_u32 s67, s67, 0
	s_cmpk_lt_u32 s3, 0xf0
	s_waitcnt vmcnt(1)
	v_mov_b32_e32 v36, v42
	s_waitcnt vmcnt(0)
	v_mov_b32_e32 v37, v12
	v_mov_b32_e32 v12, v43
	v_pk_mul_f32 v[42:43], v[62:63], v[20:21]
	v_pk_mul_f32 v[62:63], v[66:67], v[22:23]
	v_pk_fma_f32 v[20:21], v[42:43], v[98:99], v[68:69] op_sel_hi:[0,1,1]
	v_pk_fma_f32 v[20:21], v[42:43], v[38:39], v[20:21] op_sel:[1,0,0]
	v_mov_b32_e32 v32, v44
	v_pk_fma_f32 v[20:21], v[62:63], v[112:113], v[20:21] op_sel_hi:[0,1,1]
	v_pk_fma_f32 v[40:41], v[62:63], v[40:41], v[20:21] op_sel:[1,0,0]
	v_pk_fma_f32 v[20:21], v[42:43], v[118:119], v[92:93] op_sel_hi:[0,1,1]
	v_pk_fma_f32 v[20:21], v[42:43], v[54:55], v[20:21] op_sel:[1,0,0]
	v_mov_b32_e32 v33, v14
	v_pk_fma_f32 v[20:21], v[62:63], v[120:121], v[20:21] op_sel_hi:[0,1,1]
	v_pk_fma_f32 v[66:67], v[62:63], v[56:57], v[20:21] op_sel:[1,0,0]
	v_pk_fma_f32 v[20:21], v[42:43], v[126:127], v[94:95] op_sel_hi:[0,1,1]
	v_pk_fma_f32 v[20:21], v[42:43], v[50:51], v[20:21] op_sel:[1,0,0]
	v_mov_b32_e32 v14, v45
	v_pk_fma_f32 v[20:21], v[62:63], v[128:129], v[20:21] op_sel_hi:[0,1,1]
	v_pk_fma_f32 v[50:51], v[62:63], v[52:53], v[20:21] op_sel:[1,0,0]
	global_load_dwordx4 v[20:23], v3, s[12:13] offset:16
	s_waitcnt vmcnt(0)
	v_mul_f32_e32 v92, v42, v20
	v_mul_f32_e32 v52, v43, v21
	v_mul_f32_e32 v44, v62, v22
	v_mul_f32_e32 v38, v63, v23
	global_load_dwordx4 v[20:23], v3, s[70:71] offset:16
	s_waitcnt vmcnt(0)
	v_pk_mul_f32 v[42:43], v[42:43], v[20:21]
	v_add_co_u32_e32 v20, vcc, 0xffff9000, v24
	v_pk_mul_f32 v[62:63], v[62:63], v[22:23]
	s_nop 0
	v_addc_co_u32_e32 v21, vcc, -1, v25, vcc
	v_add_co_u32_e32 v22, vcc, 0xffffa000, v24
	v_mov_b32_e32 v45, v62
	s_nop 0
	v_addc_co_u32_e32 v23, vcc, -1, v25, vcc
	global_load_dword v56, v[20:21], off
	global_load_dword v57, v[22:23], off
	v_add_co_u32_e32 v20, vcc, 0xffffb000, v24
	v_mov_b32_e32 v39, v63
	s_nop 0
	v_addc_co_u32_e32 v21, vcc, -1, v25, vcc
	v_add_co_u32_e32 v22, vcc, 0xffffc000, v24
	v_mov_b32_e32 v93, v42
	s_nop 0
	v_addc_co_u32_e32 v23, vcc, -1, v25, vcc
	global_load_dword v68, v[20:21], off
	global_load_dword v69, v[22:23], off
	v_add_co_u32_e32 v20, vcc, 0xffffd000, v24
	v_mov_b32_e32 v53, v43
	s_nop 0
	v_addc_co_u32_e32 v21, vcc, -1, v25, vcc
	v_add_co_u32_e32 v22, vcc, 0xffffe000, v24
	s_nop 1
	v_addc_co_u32_e32 v23, vcc, -1, v25, vcc
	global_load_dword v54, v[20:21], off
	global_load_dword v55, v[22:23], off
	s_nop 0
	global_load_dwordx4 v[20:23], v3, s[68:69] offset:32
	s_waitcnt vmcnt(0)
	v_pk_mul_f32 v[94:95], v[56:57], v[20:21]
	v_pk_mul_f32 v[56:57], v[68:69], v[22:23]
	v_pk_fma_f32 v[20:21], v[94:95], v[114:115], v[40:41] op_sel_hi:[0,1,1]
	v_pk_fma_f32 v[22:23], v[94:95], v[122:123], v[66:67] op_sel_hi:[0,1,1]
	v_pk_fma_f32 v[98:99], v[94:95], v[130:131], v[50:51] op_sel_hi:[0,1,1]
	v_pk_fma_f32 v[20:21], v[94:95], v[46:47], v[20:21] op_sel:[1,0,0]
	v_pk_fma_f32 v[22:23], v[94:95], v[58:59], v[22:23] op_sel:[1,0,0]
	v_pk_fma_f32 v[20:21], v[56:57], v[116:117], v[20:21] op_sel_hi:[0,1,1]
	v_pk_fma_f32 v[22:23], v[56:57], v[124:125], v[22:23] op_sel_hi:[0,1,1]
	v_pk_fma_f32 v[16:17], v[94:95], v[16:17], v[98:99] op_sel:[1,0,0]
	v_pk_fma_f32 v[48:49], v[56:57], v[48:49], v[20:21] op_sel:[1,0,0]
	global_load_dwordx4 v[66:69], v3, s[12:13] offset:32
	v_pk_fma_f32 v[50:51], v[56:57], v[60:61], v[22:23] op_sel:[1,0,0]
	global_load_dwordx4 v[20:23], v3, s[70:71] offset:32
	v_pk_fma_f32 v[16:17], v[56:57], v[132:133], v[16:17] op_sel_hi:[0,1,1]
	global_load_dword v62, v[24:25], off offset:-4096
	global_load_dword v63, v[24:25], off
	v_pk_fma_f32 v[60:61], v[56:57], v[18:19], v[16:17] op_sel:[1,0,0]
	global_load_dwordx4 v[16:19], v3, s[68:69] offset:48
	v_pk_add_f32 v[58:59], v[96:97], v[92:93]
	v_lshl_add_u64 v[24:25], v[24:25], 0, s[58:59]
	v_pk_add_f32 v[58:59], v[58:59], v[52:53]
	s_waitcnt vmcnt(4)
	v_mul_f32_e32 v46, v94, v66
	v_mul_f32_e32 v40, v56, v68
	s_waitcnt vmcnt(3)
	v_pk_mul_f32 v[42:43], v[94:95], v[20:21]
	v_mul_f32_e32 v20, v57, v69
	v_mov_b32_e32 v47, v42
	v_mul_f32_e32 v42, v95, v67
	v_pk_mul_f32 v[92:93], v[56:57], v[22:23]
	global_load_dwordx4 v[66:69], v3, s[12:13] offset:48
	s_waitcnt vmcnt(1)
	v_pk_mul_f32 v[56:57], v[62:63], v[18:19]
	v_pk_mul_f32 v[62:63], v[54:55], v[16:17]
	global_load_dwordx4 v[16:19], v3, s[70:71] offset:48
	v_pk_add_f32 v[44:45], v[58:59], v[44:45]
	v_pk_fma_f32 v[30:31], v[62:63], v[30:31], v[48:49] op_sel_hi:[0,1,1]
	v_pk_fma_f32 v[34:35], v[62:63], v[34:35], v[50:51] op_sel_hi:[0,1,1]
	v_pk_add_f32 v[38:39], v[44:45], v[38:39]
	v_pk_fma_f32 v[4:5], v[62:63], v[4:5], v[30:31] op_sel:[1,0,0]
	v_pk_fma_f32 v[8:9], v[62:63], v[8:9], v[34:35] op_sel:[1,0,0]
	v_mov_b32_e32 v41, v92
	v_pk_fma_f32 v[4:5], v[56:57], v[26:27], v[4:5] op_sel_hi:[0,1,1]
	v_pk_fma_f32 v[26:27], v[56:57], v[28:29], v[8:9] op_sel_hi:[0,1,1]
	v_mov_b32_e32 v21, v93
	v_pk_fma_f32 v[8:9], v[56:57], v[6:7], v[4:5] op_sel:[1,0,0]
	v_pk_fma_f32 v[6:7], v[56:57], v[10:11], v[26:27] op_sel:[1,0,0]
	v_pk_fma_f32 v[36:37], v[62:63], v[36:37], v[60:61] op_sel_hi:[0,1,1]
	v_pk_fma_f32 v[12:13], v[62:63], v[12:13], v[36:37] op_sel:[1,0,0]
	s_waitcnt vmcnt(1)
	v_mul_f32_e32 v54, v62, v66
	v_mul_f32_e32 v52, v63, v67
	v_mul_f32_e32 v22, v56, v68
	s_waitcnt vmcnt(0)
	v_pk_mul_f32 v[16:17], v[62:63], v[16:17]
	v_pk_mul_f32 v[18:19], v[56:57], v[18:19]
	v_mov_b32_e32 v55, v16
	v_mov_b32_e32 v53, v17
	v_pk_add_f32 v[16:17], v[38:39], v[46:47]
	v_mov_b32_e32 v23, v18
	v_pk_add_f32 v[16:17], v[16:17], v[42:43]
	v_mul_f32_e32 v18, v57, v69
	v_pk_add_f32 v[10:11], v[16:17], v[40:41]
	v_pk_fma_f32 v[12:13], v[56:57], v[32:33], v[12:13] op_sel_hi:[0,1,1]
	v_pk_add_f32 v[10:11], v[10:11], v[20:21]
	v_pk_fma_f32 v[4:5], v[56:57], v[14:15], v[12:13] op_sel:[1,0,0]
	v_pk_add_f32 v[10:11], v[10:11], v[54:55]
	s_nop 0
	v_pk_add_f32 v[10:11], v[10:11], v[52:53]
	s_nop 0
	v_pk_add_f32 v[10:11], v[10:11], v[22:23]
	s_nop 0
	v_pk_add_f32 v[10:11], v[10:11], v[18:19]
	s_cbranch_scc1 .LBB0_13
	v_and_b32_e32 v2, 0x3ff, v65
	s_and_b32 s12, s93, -8
	v_lshlrev_b32_e32 v2, 11, v2
	s_mov_b32 s3, 0x1ffff
	v_cvt_pk_bf16_f32 v12, v8, v9
	v_cvt_pk_bf16_f32 v13, v6, v7
	v_cvt_pk_bf16_f32 v14, v4, v5
	v_lshl_add_u64 v[4:5], s[48:49], 0, v[2:3]
	s_ashr_i32 s13, s12, 31
	v_lshl_add_u64 v[4:5], s[12:13], 1, v[4:5]
	v_cvt_pk_bf16_f32 v15, v10, v11
	global_store_dwordx4 v[4:5], v[12:15], off
	s_xor_b32 s98, s98, 1
	s_cmp_eq_u32 s98, 1
	s_cbranch_scc0 .Lwbc_step
	v_add_u32_e32 v65, 64, v65
	v_add_u16_e32 v64, 64, v64
	s_branch .LBB0_12
.Lwbc_step:
	v_add_u32_e32 v65, s33, v65
	v_subrev_u16_e32 v64, s33, v64
	v_subrev_u32_e32 v65, 64, v65
	v_subrev_u16_e32 v64, 64, v64
	v_cmp_lt_i32_e32 vcc, s3, v65
	s_nop 1
	s_or_b64 s[64:65], vcc, s[64:65]
	s_andn2_b64 exec, exec, s[64:65]
	s_cbranch_execnz .LBB0_12
